# S27 plus DPP / permlane swaps instead of LDS bpermute for the 24 LayerNorm wave-sum steps per row of the combine+LN2 phase
# baseline (speedup 1.0000x reference)
; __device__ __forceinline__ void ln_norm_only(f32x4 (&v)[8]) {
;     float s = 0.f;
; #pragma unroll
;     for (int j = 0; j < 8; ++j) s += (v[j][0] + v[j][1]) + (v[j][2] + v[j][3]);
;     const float mean = wave_sum(s) * (1.0f / DM); float q = 0.f;
; #pragma unroll
;     for (int j = 0; j < 8; ++j) { v[j] = v[j] - mean; q += (v[j][0] * v[j][0] + v[j][1] * v[j][1]) + (v[j][2] * v[j][2] + v[j][3] * v[j][3]); }
;     const float rstd = 1.0f / sqrtf(wave_sum(q) * (1.0f / DM) + LN_EPS);
.LBB0_2525:
	v_mov_b32_e32 v106, v58
	v_mov_b32_e32 v107, v62
	v_mov_b32_e32 v110, v59
	v_mov_b32_e32 v111, v63
	v_pk_add_f32 v[106:107], v[106:107], v[110:111]
	v_mov_b32_e32 v110, v60
	v_mov_b32_e32 v111, v64
	v_mov_b32_e32 v112, v61
	v_mov_b32_e32 v113, v65
	v_pk_add_f32 v[110:111], v[110:111], v[112:113]
	v_mov_b32_e32 v112, v50
	v_pk_add_f32 v[106:107], v[106:107], v[110:111]
	v_mov_b32_e32 v110, v51
	v_mov_b32_e32 v111, v52
	v_mov_b32_e32 v113, v53
	v_pk_add_f32 v[110:111], v[110:111], v[112:113]
	v_add_f32_e32 v107, 0, v107
	v_pk_add_f32 v[110:111], v[110:111], v[110:111] op_sel_hi:[0,1]
	v_add_f32_e32 v107, v106, v107
	v_add_f32_e32 v113, v46, v47
	v_add_f32_e32 v115, v48, v49
	v_mov_b32_e32 v112, v54
	v_mov_b32_e32 v114, v55
	v_mov_b32_e32 v110, v56
	v_mov_b32_e32 v106, v57
	v_pk_add_f32 v[112:113], v[112:113], v[114:115]
	v_pk_add_f32 v[106:107], v[110:111], v[106:107]
	v_mov_b32_e32 v110, v43
	v_pk_add_f32 v[106:107], v[112:113], v[106:107]
	v_mov_b32_e32 v111, v44
	v_mov_b32_e32 v112, v42
	v_mov_b32_e32 v113, v45
	v_pk_add_f32 v[110:111], v[110:111], v[112:113]
	v_pk_add_f32 v[106:107], v[106:107], v[106:107] op_sel_hi:[0,1]
	v_pk_add_f32 v[110:111], v[110:111], v[110:111] op_sel_hi:[0,1]
	v_add_f32_e32 v113, v38, v39
	v_add_f32_e32 v115, v40, v41
	v_mov_b32_e32 v112, v34
	v_mov_b32_e32 v114, v35
	v_mov_b32_e32 v110, v36
	v_mov_b32_e32 v106, v37
	v_pk_add_f32 v[112:113], v[112:113], v[114:115]
	v_pk_add_f32 v[106:107], v[110:111], v[106:107]
	s_lshl_b32 s9, s9, 11
	v_pk_add_f32 v[106:107], v[112:113], v[106:107]
	s_and_b64 s[0:1], s[10:11], exec
	v_add_f32_e32 v106, v106, v107
	v_and_b32_e32 v107, 64, v185
	v_add_u32_e32 v113, 64, v107
	v_xor_b32_e32 v107, 1, v185
	v_cmp_lt_i32_e32 vcc, v107, v113
	s_cselect_b32 s13, s9, 0x1000
	s_mov_b32 s9, 0xf800000
	v_cndmask_b32_e32 v107, v185, v107, vcc
	v_lshlrev_b32_e32 v107, 2, v107
	s_nop 1
	v_mov_b32_dpp v108, v106 quad_perm:[1,0,3,2] row_mask:0xf bank_mask:0xf
	v_readlane_b32 s16, v249, 0
	v_readlane_b32 s22, v249, 6
	s_waitcnt lgkmcnt(0)
	v_add_f32_e32 v106, v106, v108
	v_xor_b32_e32 v108, 2, v185
	v_cmp_lt_i32_e32 vcc, v108, v113
	v_readlane_b32 s23, v249, 7
	v_readlane_b32 s17, v249, 1
	v_cndmask_b32_e32 v108, v185, v108, vcc
	v_lshlrev_b32_e32 v108, 2, v108
	s_nop 1
	v_mov_b32_dpp v110, v106 quad_perm:[2,3,0,1] row_mask:0xf bank_mask:0xf
	v_readlane_b32 s18, v249, 2
	v_readlane_b32 s19, v249, 3
	v_readlane_b32 s20, v249, 4
	v_readlane_b32 s21, v249, 5
	s_waitcnt lgkmcnt(0)
	v_add_f32_e32 v106, v106, v110
	v_xor_b32_e32 v110, 4, v185
	v_cmp_lt_i32_e32 vcc, v110, v113
	s_nop 1
	v_cndmask_b32_e32 v110, v185, v110, vcc
	v_lshlrev_b32_e32 v110, 2, v110
	s_nop 1
	v_mov_b32_dpp v111, v106 row_half_mirror row_mask:0xf bank_mask:0xf
	s_waitcnt lgkmcnt(0)
	v_add_f32_e32 v106, v106, v111
	v_xor_b32_e32 v111, 8, v185
	v_cmp_lt_i32_e32 vcc, v111, v113
	s_nop 1
	v_cndmask_b32_e32 v111, v185, v111, vcc
	v_lshlrev_b32_e32 v111, 2, v111
	s_nop 1
	v_mov_b32_dpp v112, v106 row_mirror row_mask:0xf bank_mask:0xf
	s_waitcnt lgkmcnt(0)
	v_add_f32_e32 v106, v106, v112
	v_xor_b32_e32 v112, 16, v185
	v_cmp_lt_i32_e32 vcc, v112, v113
	s_nop 1
	v_cndmask_b32_e32 v112, v185, v112, vcc
	v_lshlrev_b32_e32 v112, 2, v112
	v_mov_b32_e32 v114, v106
	v_mov_b32_e32 v244, v106
	s_nop 1
	v_permlane16_swap_b32_e32 v244, v114
	s_waitcnt lgkmcnt(0)
	v_add_f32_e32 v106, v244, v114
	v_xor_b32_e32 v114, 32, v185
	v_cmp_lt_i32_e32 vcc, v114, v113
	s_nop 1
	v_cndmask_b32_e32 v113, v185, v114, vcc
	v_lshlrev_b32_e32 v113, 2, v113
	v_mov_b32_e32 v114, v106
	v_mov_b32_e32 v244, v106
	s_nop 1
	v_permlane32_swap_b32_e32 v244, v114
	s_waitcnt lgkmcnt(0)
	v_add_f32_e32 v122, v244, v114
	v_fmamk_f32 v63, v122, 0xba000000, v63
	v_fmamk_f32 v59, v122, 0xba000000, v59
	v_fmamk_f32 v65, v122, 0xba000000, v65
	v_fmac_f32_e32 v62, 0xba000000, v122
	v_fmamk_f32 v61, v122, 0xba000000, v61
	v_fmac_f32_e32 v58, 0xba000000, v122
	v_mov_b32_e32 v116, v63
	v_mov_b32_e32 v117, v59
	v_fmamk_f32 v64, v122, 0xba000000, v64
	v_fmamk_f32 v60, v122, 0xba000000, v60
	v_mov_b32_e32 v114, v62
	v_mov_b32_e32 v115, v58
	v_pk_mul_f32 v[116:117], v[116:117], v[116:117]
	v_mov_b32_e32 v118, v65
	v_mov_b32_e32 v119, v61
	v_pk_fma_f32 v[114:115], v[114:115], v[114:115], v[116:117]
	v_mov_b32_e32 v116, v64
	v_mov_b32_e32 v117, v60
	v_pk_mul_f32 v[118:119], v[118:119], v[118:119]
	v_fmamk_f32 v51, v122, 0xba000000, v51
	v_pk_fma_f32 v[116:117], v[116:117], v[116:117], v[118:119]
	v_fmamk_f32 v50, v122, 0xba000000, v50
	v_fmamk_f32 v53, v122, 0xba000000, v53
	v_fmac_f32_e32 v52, 0xba000000, v122
	v_pk_add_f32 v[114:115], v[114:115], v[116:117]
	v_pk_mul_f32 v[116:117], v[52:53], v[52:53]
	v_pk_mul_f32 v[118:119], v[50:51], v[50:51]
	v_fmamk_f32 v46, v122, 0xba000000, v46
	v_pk_mov_b32 v[120:121], v[118:119], v[116:117] op_sel:[1,0]
	v_mov_b32_e32 v119, v117
	v_fmamk_f32 v47, v122, 0xba000000, v47
	v_fmac_f32_e32 v48, 0xba000000, v122
	v_mul_f32_e32 v106, v46, v46
	v_pk_add_f32 v[116:117], v[120:121], v[118:119]
	v_fmamk_f32 v49, v122, 0xba000000, v49
	v_pk_fma_f32 v[118:119], v[46:47], v[46:47], v[106:107] op_sel_hi:[1,1,0]
	v_mul_f32_e32 v106, v48, v48
	v_pk_add_f32 v[114:115], v[114:115], v[114:115] op_sel_hi:[0,1]
	v_pk_add_f32 v[116:117], v[116:117], v[116:117] op_sel_hi:[0,1]
	v_pk_fma_f32 v[120:121], v[48:49], v[48:49], v[106:107] op_sel_hi:[1,1,0]
	v_fmamk_f32 v57, v122, 0xba000000, v57
	v_fmamk_f32 v56, v122, 0xba000000, v56
	v_fmamk_f32 v55, v122, 0xba000000, v55
	v_fmac_f32_e32 v54, 0xba000000, v122
	v_mul_f32_e32 v118, v54, v54
	v_mul_f32_e32 v120, v55, v55
	v_mul_f32_e32 v116, v56, v56
	v_mul_f32_e32 v114, v57, v57
	v_pk_add_f32 v[118:119], v[118:119], v[120:121]
; #define LAS __attribute__((address_space(3)))
; __device__ __forceinline__ void ln_norm_only(f32x4 (&v)[8]) {
;     ...
;     const float mean = wave_sum(s) * (1.0f / DM); float q = 0.f;
; #pragma unroll
;     for (int j = 0; j < 8; ++j) { v[j] = v[j] - mean; q += (v[j][0] * v[j][0] + v[j][1] * v[j][1]) + (v[j][2] * v[j][2] + v[j][3] * v[j][3]); }
;     const float rstd = 1.0f / sqrtf(wave_sum(q) * (1.0f / DM) + LN_EPS);
; #pragma unroll
;     for (int j = 0; j < 8; ++j) v[j] = v[j] * rstd;
; __device__ __forceinline__ void combine_ln2(Frame& F, int l, int nrows) {
;     ...
;         ln_norm_only(xcur);
;         asm volatile("" ::: "memory");
; #pragma unroll
;         for (int j = 0; j < 8; ++j) { const int cc = 256 * j + 4 * F.lane;
;             xcur[j] = (xcur[j] * *(const LAS f32x4*)(PLW1 + cc) + *(const LAS f32x4*)(PLB1 + cc)) * ALPHA_RES + *(const LAS f32x4*)(g2 + cc) * moe[j]; }
	v_pk_add_f32 v[114:115], v[116:117], v[114:115]
	v_fmamk_f32 v43, v122, 0xba000000, v43
	v_fmamk_f32 v42, v122, 0xba000000, v42
	v_fmamk_f32 v45, v122, 0xba000000, v45
	v_fmac_f32_e32 v44, 0xba000000, v122
	v_pk_add_f32 v[114:115], v[118:119], v[114:115]
	v_pk_mul_f32 v[116:117], v[44:45], v[44:45]
	v_pk_mul_f32 v[118:119], v[42:43], v[42:43]
	v_fmamk_f32 v38, v122, 0xba000000, v38
	v_pk_mov_b32 v[120:121], v[118:119], v[116:117] op_sel:[1,0]
	v_mov_b32_e32 v119, v117
	v_fmamk_f32 v39, v122, 0xba000000, v39
	v_fmac_f32_e32 v40, 0xba000000, v122
	v_mul_f32_e32 v106, v38, v38
	v_pk_add_f32 v[116:117], v[120:121], v[118:119]
	v_fmamk_f32 v41, v122, 0xba000000, v41
	v_pk_fma_f32 v[118:119], v[38:39], v[38:39], v[106:107] op_sel_hi:[1,1,0]
	v_mul_f32_e32 v106, v40, v40
	v_pk_add_f32 v[114:115], v[114:115], v[114:115] op_sel_hi:[0,1]
	v_pk_add_f32 v[116:117], v[116:117], v[116:117] op_sel_hi:[0,1]
	v_pk_fma_f32 v[120:121], v[40:41], v[40:41], v[106:107] op_sel_hi:[1,1,0]
	v_fmamk_f32 v37, v122, 0xba000000, v37
	v_fmamk_f32 v36, v122, 0xba000000, v36
	v_fmamk_f32 v35, v122, 0xba000000, v35
	v_fmac_f32_e32 v34, 0xba000000, v122
	v_mul_f32_e32 v118, v34, v34
	v_mul_f32_e32 v120, v35, v35
	v_mul_f32_e32 v116, v36, v36
	v_mul_f32_e32 v114, v37, v37
	v_pk_add_f32 v[118:119], v[118:119], v[120:121]
	v_pk_add_f32 v[114:115], v[116:117], v[114:115]
	s_nop 0
	v_pk_add_f32 v[114:115], v[118:119], v[114:115]
	s_nop 0
	v_add_f32_e32 v106, v114, v115
	s_nop 1
	v_mov_b32_dpp v114, v106 quad_perm:[1,0,3,2] row_mask:0xf bank_mask:0xf
	s_waitcnt lgkmcnt(0)
	v_add_f32_e32 v106, v106, v114
	s_nop 1
	v_mov_b32_dpp v114, v106 quad_perm:[2,3,0,1] row_mask:0xf bank_mask:0xf
	s_waitcnt lgkmcnt(0)
	v_add_f32_e32 v106, v106, v114
	s_nop 1
	v_mov_b32_dpp v114, v106 row_half_mirror row_mask:0xf bank_mask:0xf
	s_waitcnt lgkmcnt(0)
	v_add_f32_e32 v106, v106, v114
	s_nop 1
	v_mov_b32_dpp v114, v106 row_mirror row_mask:0xf bank_mask:0xf
	s_waitcnt lgkmcnt(0)
	v_add_f32_e32 v106, v106, v114
	v_mov_b32_e32 v114, v106
	v_mov_b32_e32 v244, v106
	s_nop 1
	v_permlane16_swap_b32_e32 v244, v114
	s_waitcnt lgkmcnt(0)
	v_add_f32_e32 v106, v244, v114
	v_mov_b32_e32 v114, v106
	v_mov_b32_e32 v244, v106
	s_nop 1
	v_permlane32_swap_b32_e32 v244, v114
	s_waitcnt lgkmcnt(0)
	v_add_f32_e32 v106, v244, v114
	v_fmamk_f32 v106, v106, 0x3a000000, v179
	v_cmp_gt_f32_e32 vcc, s9, v106
	v_mul_f32_e32 v114, 0x4f800000, v106
	s_nop 0
	v_cndmask_b32_e32 v106, v106, v114, vcc
	v_sqrt_f32_e32 v114, v106
	s_nop 0
	v_add_u32_e32 v115, -1, v114
	v_fma_f32 v116, -v115, v114, v106
	v_cmp_ge_f32_e64 s[0:1], 0, v116
	v_add_u32_e32 v116, 1, v114
	s_nop 0
	v_cndmask_b32_e64 v115, v114, v115, s[0:1]
	v_fma_f32 v114, -v116, v114, v106
	v_cmp_lt_f32_e64 s[0:1], 0, v114
	s_nop 1
	v_cndmask_b32_e64 v114, v115, v116, s[0:1]
	v_mul_f32_e32 v115, 0x37800000, v114
	v_cndmask_b32_e32 v114, v114, v115, vcc
	v_cmp_class_f32_e32 vcc, v106, v180
	s_nop 1
	v_cndmask_b32_e32 v106, v114, v106, vcc
	v_div_scale_f32 v114, s[0:1], v106, v106, 1.0
	v_rcp_f32_e32 v115, v114
	s_mov_b32 s0, 0x3fb504f3
	v_fma_f32 v116, -v114, v115, 1.0
	v_fmac_f32_e32 v115, v116, v115
	v_div_scale_f32 v116, vcc, 1.0, v106, 1.0
	v_mul_f32_e32 v117, v116, v115
	v_fma_f32 v118, -v114, v117, v116
	v_fmac_f32_e32 v117, v118, v115
	v_fma_f32 v114, -v114, v117, v116
	v_div_fmas_f32 v114, v114, v115, v117
	v_div_fixup_f32 v106, v114, v106, 1.0
	v_pk_mul_f32 v[114:115], v[62:63], v[106:107] op_sel_hi:[1,0]
	v_pk_mul_f32 v[118:119], v[58:59], v[106:107] op_sel_hi:[1,0]
	v_pk_mul_f32 v[122:123], v[50:51], v[106:107] op_sel_hi:[1,0]
	v_pk_mul_f32 v[124:125], v[52:53], v[106:107] op_sel_hi:[1,0]
	v_pk_mul_f32 v[58:59], v[56:57], v[106:107] op_sel_hi:[1,0]
	v_pk_mul_f32 v[56:57], v[38:39], v[106:107] op_sel_hi:[1,0]
	v_pk_mul_f32 v[62:63], v[40:41], v[106:107] op_sel_hi:[1,0]
	v_pk_mul_f32 v[50:51], v[34:35], v[106:107] op_sel_hi:[1,0]
	v_pk_mul_f32 v[52:53], v[36:37], v[106:107] op_sel_hi:[1,0]
	ds_read_b128 v[34:37], v140
	ds_read_b128 v[38:41], v141
	v_pk_mul_f32 v[116:117], v[64:65], v[106:107] op_sel_hi:[1,0]
	v_pk_mul_f32 v[120:121], v[60:61], v[106:107] op_sel_hi:[1,0]
	v_pk_mul_f32 v[126:127], v[46:47], v[106:107] op_sel_hi:[1,0]
	v_pk_mul_f32 v[128:129], v[48:49], v[106:107] op_sel_hi:[1,0]
	v_pk_mul_f32 v[48:49], v[54:55], v[106:107] op_sel_hi:[1,0]
	v_pk_mul_f32 v[60:61], v[42:43], v[106:107] op_sel_hi:[1,0]
	v_pk_mul_f32 v[64:65], v[44:45], v[106:107] op_sel_hi:[1,0]
	s_waitcnt lgkmcnt(0)
	v_pk_fma_f32 v[36:37], v[36:37], v[116:117], v[40:41]
	v_pk_fma_f32 v[34:35], v[34:35], v[114:115], v[38:39]
	v_lshl_add_u32 v106, s13, 2, v139
	v_pk_mul_f32 v[40:41], v[34:35], s[0:1] op_sel_hi:[1,0]
	v_pk_mul_f32 v[34:35], v[36:37], s[0:1] op_sel_hi:[1,0]
	ds_read_b128 v[36:39], v106
	s_waitcnt lgkmcnt(0)
	v_pk_fma_f32 v[34:35], v[104:105], v[38:39], v[34:35]
	v_pk_fma_f32 v[36:37], v[102:103], v[36:37], v[40:41]
	ds_read_b128 v[38:41], v142
	ds_read_b128 v[42:45], v143
	s_waitcnt lgkmcnt(0)
	v_pk_fma_f32 v[40:41], v[40:41], v[120:121], v[44:45]
	v_pk_fma_f32 v[38:39], v[38:39], v[118:119], v[42:43]
	s_nop 0
	v_pk_mul_f32 v[44:45], v[38:39], s[0:1] op_sel_hi:[1,0]
	v_pk_mul_f32 v[38:39], v[40:41], s[0:1] op_sel_hi:[1,0]
	ds_read_b128 v[40:43], v106 offset:1024
	s_waitcnt lgkmcnt(0)
	v_pk_fma_f32 v[38:39], v[100:101], v[42:43], v[38:39]
	v_pk_fma_f32 v[42:43], v[98:99], v[40:41], v[44:45]
	ds_read_b128 v[44:47], v144
	ds_read_b128 v[98:101], v154
	s_waitcnt lgkmcnt(0)
	v_pk_fma_f32 v[44:45], v[44:45], v[122:123], v[98:99]
	v_pk_fma_f32 v[40:41], v[46:47], v[124:125], v[100:101]
	v_pk_mul_f32 v[54:55], v[44:45], s[0:1] op_sel_hi:[1,0]
	ds_read_b128 v[44:47], v106 offset:2048
	v_pk_mul_f32 v[40:41], v[40:41], s[0:1] op_sel_hi:[1,0]
	s_waitcnt lgkmcnt(0)
; #define LAS __attribute__((address_space(3)))
; __device__ __forceinline__ void ln_inplace_lds(f32x4 (&v)[8], const LAS float* w, const LAS float* b, int lane) {
;     float s = 0.f;
; #pragma unroll
;     for (int j = 0; j < 8; ++j) s += (v[j][0] + v[j][1]) + (v[j][2] + v[j][3]);
;     const float mean = wave_sum(s) * (1.0f / DM); float q = 0.f;
; #pragma unroll
;     for (int j = 0; j < 8; ++j) { v[j] = v[j] - mean; q += (v[j][0] * v[j][0] + v[j][1] * v[j][1]) + (v[j][2] * v[j][2] + v[j][3] * v[j][3]); }
; __device__ __forceinline__ void combine_ln2(Frame& F, int l, int nrows) {
;     ...
; #pragma unroll
;         for (int j = 0; j < 8; ++j) { const int cc = 256 * j + 4 * F.lane;
;             xcur[j] = (xcur[j] * *(const LAS f32x4*)(PLW1 + cc) + *(const LAS f32x4*)(PLB1 + cc)) * ALPHA_RES + *(const LAS f32x4*)(g2 + cc) * moe[j]; }
	v_pk_fma_f32 v[44:45], v[94:95], v[44:45], v[54:55]
	v_pk_fma_f32 v[40:41], v[96:97], v[46:47], v[40:41]
	ds_read_b128 v[94:97], v155
	ds_read_b128 v[98:101], v156
	s_waitcnt lgkmcnt(0)
	v_pk_fma_f32 v[46:47], v[96:97], v[128:129], v[100:101]
	v_pk_fma_f32 v[54:55], v[94:95], v[126:127], v[98:99]
	ds_read_b128 v[94:97], v106 offset:3072
	v_pk_mul_f32 v[54:55], v[54:55], s[0:1] op_sel_hi:[1,0]
	v_pk_mul_f32 v[46:47], v[46:47], s[0:1] op_sel_hi:[1,0]
	s_waitcnt lgkmcnt(0)
	v_pk_fma_f32 v[54:55], v[90:91], v[94:95], v[54:55]
	v_pk_fma_f32 v[46:47], v[92:93], v[96:97], v[46:47]
	ds_read_b128 v[90:93], v157
	ds_read_b128 v[94:97], v158
	s_waitcnt lgkmcnt(0)
	v_pk_fma_f32 v[58:59], v[92:93], v[58:59], v[96:97]
	v_pk_fma_f32 v[48:49], v[90:91], v[48:49], v[94:95]
	ds_read_b128 v[90:93], v106 offset:4096
	v_pk_mul_f32 v[94:95], v[48:49], s[0:1] op_sel_hi:[1,0]
	v_pk_mul_f32 v[48:49], v[58:59], s[0:1] op_sel_hi:[1,0]
	s_waitcnt lgkmcnt(0)
	v_pk_fma_f32 v[58:59], v[86:87], v[90:91], v[94:95]
	v_pk_fma_f32 v[48:49], v[88:89], v[92:93], v[48:49]
	ds_read_b128 v[86:89], v159
	ds_read_b128 v[90:93], v160
	s_waitcnt lgkmcnt(0)
	v_pk_fma_f32 v[64:65], v[88:89], v[64:65], v[92:93]
	v_pk_fma_f32 v[60:61], v[86:87], v[60:61], v[90:91]
	ds_read_b128 v[86:89], v106 offset:5120
	v_pk_mul_f32 v[90:91], v[60:61], s[0:1] op_sel_hi:[1,0]
	v_pk_mul_f32 v[60:61], v[64:65], s[0:1] op_sel_hi:[1,0]
	s_waitcnt lgkmcnt(0)
	v_pk_fma_f32 v[64:65], v[82:83], v[86:87], v[90:91]
	v_pk_fma_f32 v[60:61], v[84:85], v[88:89], v[60:61]
	ds_read_b128 v[82:85], v161
	ds_read_b128 v[86:89], v162
	s_waitcnt lgkmcnt(0)
	v_pk_fma_f32 v[62:63], v[84:85], v[62:63], v[88:89]
	v_pk_fma_f32 v[56:57], v[82:83], v[56:57], v[86:87]
	ds_read_b128 v[82:85], v106 offset:6144
	v_pk_mul_f32 v[56:57], v[56:57], s[0:1] op_sel_hi:[1,0]
	v_pk_mul_f32 v[62:63], v[62:63], s[0:1] op_sel_hi:[1,0]
	s_waitcnt lgkmcnt(0)
	v_pk_fma_f32 v[78:79], v[78:79], v[82:83], v[56:57]
	v_pk_fma_f32 v[62:63], v[80:81], v[84:85], v[62:63]
	ds_read_b128 v[80:83], v163
	ds_read_b128 v[84:87], v164
	s_waitcnt lgkmcnt(0)
	v_pk_fma_f32 v[52:53], v[82:83], v[52:53], v[86:87]
	v_pk_fma_f32 v[50:51], v[80:81], v[50:51], v[84:85]
	v_pk_mul_f32 v[80:81], v[52:53], s[0:1] op_sel_hi:[1,0]
	v_pk_mul_f32 v[56:57], v[50:51], s[0:1] op_sel_hi:[1,0]
	ds_read_b128 v[50:53], v106 offset:7168
	s_waitcnt lgkmcnt(0)
	v_pk_fma_f32 v[76:77], v[76:77], v[52:53], v[80:81]
	v_pk_fma_f32 v[74:75], v[74:75], v[50:51], v[56:57]
	v_mov_b32_e32 v50, v42
	v_mov_b32_e32 v51, v36
	v_mov_b32_e32 v52, v43
	v_mov_b32_e32 v53, v37
	v_pk_add_f32 v[50:51], v[50:51], v[52:53]
	v_mov_b32_e32 v52, v38
	v_mov_b32_e32 v53, v34
	v_mov_b32_e32 v56, v39
	v_mov_b32_e32 v57, v35
	v_pk_add_f32 v[52:53], v[52:53], v[56:57]
	v_mov_b32_e32 v56, v44
	v_pk_add_f32 v[50:51], v[50:51], v[52:53]
	v_pk_mov_b32 v[52:53], v[44:45], v[40:41] op_sel:[1,0]
	v_mov_b32_e32 v57, v41
	v_pk_add_f32 v[52:53], v[52:53], v[56:57]
	v_add_f32_e32 v51, 0, v51
	v_pk_add_f32 v[52:53], v[52:53], v[52:53] op_sel_hi:[0,1]
	v_add_f32_e32 v51, v50, v51
	v_add_f32_e32 v57, v54, v55
	v_add_f32_e32 v81, v46, v47
	v_mov_b32_e32 v56, v58
	v_mov_b32_e32 v80, v59
	v_mov_b32_e32 v52, v48
	v_mov_b32_e32 v50, v49
	v_pk_add_f32 v[56:57], v[56:57], v[80:81]
	v_pk_add_f32 v[50:51], v[52:53], v[50:51]
	v_pk_mov_b32 v[52:53], v[64:65], v[60:61] op_sel:[1,0]
	v_pk_add_f32 v[50:51], v[56:57], v[50:51]
	v_mov_b32_e32 v56, v64
	v_mov_b32_e32 v57, v61
	v_pk_add_f32 v[52:53], v[52:53], v[56:57]
	v_pk_add_f32 v[50:51], v[50:51], v[50:51] op_sel_hi:[0,1]
	v_pk_add_f32 v[52:53], v[52:53], v[52:53] op_sel_hi:[0,1]
	v_add_f32_e32 v57, v78, v79
	v_add_f32_e32 v81, v62, v63
	v_mov_b32_e32 v56, v74
	v_mov_b32_e32 v80, v75
	v_mov_b32_e32 v52, v76
	v_mov_b32_e32 v50, v77
	v_pk_add_f32 v[56:57], v[56:57], v[80:81]
	v_pk_add_f32 v[50:51], v[52:53], v[50:51]
	s_nop 0
	v_pk_add_f32 v[50:51], v[56:57], v[50:51]
	s_nop 0
	v_add_f32_e32 v50, v50, v51
	s_nop 1
	v_mov_b32_dpp v51, v50 quad_perm:[1,0,3,2] row_mask:0xf bank_mask:0xf
	s_waitcnt lgkmcnt(0)
	v_add_f32_e32 v50, v50, v51
	s_nop 1
	v_mov_b32_dpp v51, v50 quad_perm:[2,3,0,1] row_mask:0xf bank_mask:0xf
	s_waitcnt lgkmcnt(0)
	v_add_f32_e32 v50, v50, v51
	s_nop 1
	v_mov_b32_dpp v51, v50 row_half_mirror row_mask:0xf bank_mask:0xf
	s_waitcnt lgkmcnt(0)
	v_add_f32_e32 v50, v50, v51
	s_nop 1
	v_mov_b32_dpp v51, v50 row_mirror row_mask:0xf bank_mask:0xf
	s_waitcnt lgkmcnt(0)
	v_add_f32_e32 v50, v50, v51
	v_mov_b32_e32 v51, v50
	v_mov_b32_e32 v244, v50
	s_nop 1
	v_permlane16_swap_b32_e32 v244, v51
	s_waitcnt lgkmcnt(0)
	v_add_f32_e32 v50, v244, v51
	v_mov_b32_e32 v51, v50
	v_mov_b32_e32 v244, v50
	s_nop 1
	v_permlane32_swap_b32_e32 v244, v51
	s_waitcnt lgkmcnt(0)
; #define LAS __attribute__((address_space(3)))
; __device__ __forceinline__ void ln_inplace_lds(f32x4 (&v)[8], const LAS float* w, const LAS float* b, int lane) {
;     ...
;     const float mean = wave_sum(s) * (1.0f / DM); float q = 0.f;
; #pragma unroll
;     for (int j = 0; j < 8; ++j) { v[j] = v[j] - mean; q += (v[j][0] * v[j][0] + v[j][1] * v[j][1]) + (v[j][2] * v[j][2] + v[j][3] * v[j][3]); }
;     const float rstd = 1.0f / sqrtf(wave_sum(q) * (1.0f / DM) + LN_EPS);
; #pragma unroll
;     for (int j = 0; j < 8; ++j) { const int c = 256 * j + 4 * lane; v[j] = v[j] * rstd * *(const LAS f32x4*)(w + c) + *(const LAS f32x4*)(b + c); }
	v_add_f32_e32 v82, v244, v51
	v_fmamk_f32 v37, v82, 0xba000000, v37
	v_fmamk_f32 v43, v82, 0xba000000, v43
	v_fmamk_f32 v35, v82, 0xba000000, v35
	v_fmac_f32_e32 v36, 0xba000000, v82
	v_fmamk_f32 v39, v82, 0xba000000, v39
	v_fmac_f32_e32 v42, 0xba000000, v82
	v_mov_b32_e32 v52, v37
	v_mov_b32_e32 v53, v43
	v_fmac_f32_e32 v34, 0xba000000, v82
	v_fmac_f32_e32 v38, 0xba000000, v82
	v_mov_b32_e32 v50, v36
	v_mov_b32_e32 v51, v42
	v_pk_mul_f32 v[52:53], v[52:53], v[52:53]
	v_mov_b32_e32 v56, v35
	v_mov_b32_e32 v57, v39
	v_pk_fma_f32 v[50:51], v[50:51], v[50:51], v[52:53]
	v_mov_b32_e32 v52, v34
	v_mov_b32_e32 v53, v38
	v_pk_mul_f32 v[56:57], v[56:57], v[56:57]
	v_fmamk_f32 v45, v82, 0xba000000, v45
	v_pk_fma_f32 v[52:53], v[52:53], v[52:53], v[56:57]
	v_fmac_f32_e32 v44, 0xba000000, v82
	v_pk_add_f32 v[50:51], v[50:51], v[52:53]
	v_fmamk_f32 v41, v82, 0xba000000, v41
	v_fmac_f32_e32 v40, 0xba000000, v82
	v_pk_add_f32 v[50:51], v[50:51], v[50:51] op_sel_hi:[0,1]
	v_pk_mul_f32 v[52:53], v[40:41], v[40:41]
	v_pk_mul_f32 v[56:57], v[44:45], v[44:45]
	v_fmac_f32_e32 v54, 0xba000000, v82
	v_pk_mov_b32 v[80:81], v[56:57], v[52:53] op_sel:[1,0]
	v_mov_b32_e32 v57, v53
	v_fmamk_f32 v55, v82, 0xba000000, v55
	v_fmac_f32_e32 v46, 0xba000000, v82
	v_mul_f32_e32 v50, v54, v54
	v_pk_add_f32 v[52:53], v[80:81], v[56:57]
	v_fmamk_f32 v47, v82, 0xba000000, v47
	v_pk_fma_f32 v[56:57], v[54:55], v[54:55], v[50:51] op_sel_hi:[1,1,0]
	v_mul_f32_e32 v50, v46, v46
	v_pk_add_f32 v[52:53], v[52:53], v[52:53] op_sel_hi:[0,1]
	v_pk_fma_f32 v[80:81], v[46:47], v[46:47], v[50:51] op_sel_hi:[1,1,0]
	v_fmamk_f32 v49, v82, 0xba000000, v49
	v_fmac_f32_e32 v48, 0xba000000, v82
	v_fmamk_f32 v59, v82, 0xba000000, v59
	v_fmac_f32_e32 v58, 0xba000000, v82
	v_mul_f32_e32 v56, v58, v58
	v_mul_f32_e32 v80, v59, v59
	v_mul_f32_e32 v52, v48, v48
	v_mul_f32_e32 v50, v49, v49
	v_pk_add_f32 v[56:57], v[56:57], v[80:81]
	v_pk_add_f32 v[50:51], v[52:53], v[50:51]
	v_fmamk_f32 v65, v82, 0xba000000, v65
	v_pk_add_f32 v[50:51], v[56:57], v[50:51]
	v_fmac_f32_e32 v64, 0xba000000, v82
	v_fmamk_f32 v61, v82, 0xba000000, v61
	v_fmac_f32_e32 v60, 0xba000000, v82
	v_pk_add_f32 v[50:51], v[50:51], v[50:51] op_sel_hi:[0,1]
	v_pk_mul_f32 v[52:53], v[60:61], v[60:61]
	v_pk_mul_f32 v[56:57], v[64:65], v[64:65]
	v_fmac_f32_e32 v78, 0xba000000, v82
	v_pk_mov_b32 v[80:81], v[56:57], v[52:53] op_sel:[1,0]
	v_mov_b32_e32 v57, v53
	v_fmamk_f32 v79, v82, 0xba000000, v79
	v_fmac_f32_e32 v62, 0xba000000, v82
	v_mul_f32_e32 v50, v78, v78
	v_pk_add_f32 v[52:53], v[80:81], v[56:57]
	v_fmamk_f32 v63, v82, 0xba000000, v63
	v_pk_fma_f32 v[56:57], v[78:79], v[78:79], v[50:51] op_sel_hi:[1,1,0]
	v_mul_f32_e32 v50, v62, v62
	v_pk_add_f32 v[52:53], v[52:53], v[52:53] op_sel_hi:[0,1]
	v_pk_fma_f32 v[80:81], v[62:63], v[62:63], v[50:51] op_sel_hi:[1,1,0]
	v_fmamk_f32 v77, v82, 0xba000000, v77
	v_fmac_f32_e32 v76, 0xba000000, v82
	v_fmamk_f32 v75, v82, 0xba000000, v75
	v_fmac_f32_e32 v74, 0xba000000, v82
	v_mul_f32_e32 v56, v74, v74
	v_mul_f32_e32 v80, v75, v75
	v_mul_f32_e32 v52, v76, v76
	v_mul_f32_e32 v50, v77, v77
	v_pk_add_f32 v[56:57], v[56:57], v[80:81]
	v_pk_add_f32 v[50:51], v[52:53], v[50:51]
	s_nop 0
	v_pk_add_f32 v[50:51], v[56:57], v[50:51]
	s_nop 0
	v_add_f32_e32 v50, v50, v51
	s_nop 1
	v_mov_b32_dpp v51, v50 quad_perm:[1,0,3,2] row_mask:0xf bank_mask:0xf
	s_waitcnt lgkmcnt(0)
	v_add_f32_e32 v50, v50, v51
	s_nop 1
	v_mov_b32_dpp v51, v50 quad_perm:[2,3,0,1] row_mask:0xf bank_mask:0xf
	s_waitcnt lgkmcnt(0)
	v_add_f32_e32 v50, v50, v51
	s_nop 1
	v_mov_b32_dpp v51, v50 row_half_mirror row_mask:0xf bank_mask:0xf
	s_waitcnt lgkmcnt(0)
	v_add_f32_e32 v50, v50, v51
	s_nop 1
	v_mov_b32_dpp v51, v50 row_mirror row_mask:0xf bank_mask:0xf
	s_waitcnt lgkmcnt(0)
	v_add_f32_e32 v50, v50, v51
	v_mov_b32_e32 v51, v50
	v_mov_b32_e32 v244, v50
	s_nop 1
	v_permlane16_swap_b32_e32 v244, v51
	s_waitcnt lgkmcnt(0)
	v_add_f32_e32 v50, v244, v51
	v_mov_b32_e32 v51, v50
	v_mov_b32_e32 v244, v50
	s_nop 1
	v_permlane32_swap_b32_e32 v244, v51
	s_waitcnt lgkmcnt(0)
	v_add_f32_e32 v50, v244, v51
	v_fmamk_f32 v50, v50, 0x3a000000, v179
	v_cmp_gt_f32_e32 vcc, s9, v50
	v_mul_f32_e32 v51, 0x4f800000, v50
	s_ashr_i32 s9, s8, 31
	v_cndmask_b32_e32 v50, v50, v51, vcc
	v_sqrt_f32_e32 v51, v50
	s_nop 0
	v_add_u32_e32 v52, -1, v51
	v_fma_f32 v53, -v52, v51, v50
	v_cmp_ge_f32_e64 s[0:1], 0, v53
	v_add_u32_e32 v53, 1, v51
	s_nop 0
	v_cndmask_b32_e64 v52, v51, v52, s[0:1]
	v_fma_f32 v51, -v53, v51, v50
	v_cmp_lt_f32_e64 s[0:1], 0, v51
	s_nop 1
	v_cndmask_b32_e64 v51, v52, v53, s[0:1]
	v_mul_f32_e32 v52, 0x37800000, v51
	v_cndmask_b32_e32 v51, v51, v52, vcc
	v_cmp_class_f32_e32 vcc, v50, v180
	s_and_b64 s[0:1], s[10:11], exec
	v_readlane_b32 s10, v251, 30
	v_cndmask_b32_e32 v50, v51, v50, vcc
	v_div_scale_f32 v51, s[0:1], v50, v50, 1.0
	v_rcp_f32_e32 v52, v51
	s_cselect_b32 s1, s9, 0
	s_cselect_b32 s0, s8, s5
	v_readlane_b32 s5, v251, 31
	v_fma_f32 v53, -v51, v52, 1.0
	v_fmac_f32_e32 v52, v53, v52
	v_div_scale_f32 v53, vcc, 1.0, v50, 1.0
	v_mul_f32_e32 v56, v53, v52
	v_fma_f32 v57, -v51, v56, v53
	v_fmac_f32_e32 v56, v57, v52
	v_fma_f32 v51, -v51, v56, v53
	v_div_fmas_f32 v51, v51, v52, v56
	v_div_fixup_f32 v80, v51, v50, 1.0
	v_pk_mul_f32 v[56:57], v[36:37], v[80:81] op_sel_hi:[1,0]
	v_pk_mul_f32 v[82:83], v[34:35], v[80:81] op_sel_hi:[1,0]
	ds_read_b128 v[34:37], v139 offset:24576
	ds_read_b128 v[50:53], v139 offset:32768
	v_pk_mul_f32 v[42:43], v[42:43], v[80:81] op_sel_hi:[1,0]
	v_pk_mul_f32 v[38:39], v[38:39], v[80:81] op_sel_hi:[1,0]
	v_pk_mul_f32 v[46:47], v[46:47], v[80:81] op_sel_hi:[1,0]
	v_pk_mul_f32 v[58:59], v[58:59], v[80:81] op_sel_hi:[1,0]
	s_waitcnt lgkmcnt(0)
; #define LAS __attribute__((address_space(3)))
; __device__ __forceinline__ void ln_inplace_lds(f32x4 (&v)[8], const LAS float* w, const LAS float* b, int lane) {
;     ...
;     const float rstd = 1.0f / sqrtf(wave_sum(q) * (1.0f / DM) + LN_EPS);
; #pragma unroll
;     for (int j = 0; j < 8; ++j) { const int c = 256 * j + 4 * lane; v[j] = v[j] * rstd * *(const LAS f32x4*)(w + c) + *(const LAS f32x4*)(b + c); }
; __device__ __forceinline__ void combine_ln2(Frame& F, int l, int nrows) {
;     ...
;         float* orow = lat ? F.out + (size_t)row * DM : (float*)(F.ws + WS_R2C) + (size_t)(row - NLAT) * DM;
; #pragma unroll
;         for (int j = 0; j < 8; ++j) *(f32x4*)(orow + 256 * j + 4 * F.lane) = xcur[j];
	v_pk_fma_f32 v[36:37], v[36:37], v[82:83], v[52:53]
	v_pk_fma_f32 v[34:35], v[34:35], v[56:57], v[50:51]
	ds_read_b128 v[50:53], v139 offset:25600
	ds_read_b128 v[82:85], v139 offset:33792
	v_pk_mul_f32 v[56:57], v[44:45], v[80:81] op_sel_hi:[1,0]
	v_pk_mul_f32 v[64:65], v[64:65], v[80:81] op_sel_hi:[1,0]
	v_pk_mul_f32 v[78:79], v[78:79], v[80:81] op_sel_hi:[1,0]
	s_cselect_b32 s5, s23, s5
	s_waitcnt lgkmcnt(0)
	v_pk_fma_f32 v[52:53], v[52:53], v[38:39], v[84:85]
	v_pk_fma_f32 v[50:51], v[50:51], v[42:43], v[82:83]
	v_pk_mul_f32 v[82:83], v[40:41], v[80:81] op_sel_hi:[1,0]
	ds_read_b128 v[38:41], v139 offset:26624
	ds_read_b128 v[42:45], v139 offset:34816
	s_cselect_b32 s10, s22, s10
	s_lshl_b64 s[0:1], s[0:1], 13
	s_add_u32 s0, s10, s0
	s_addc_u32 s1, s5, s1
	s_waitcnt lgkmcnt(0)
	v_pk_fma_f32 v[40:41], v[40:41], v[82:83], v[44:45]
	v_pk_fma_f32 v[38:39], v[38:39], v[56:57], v[42:43]
	v_pk_mul_f32 v[82:83], v[54:55], v[80:81] op_sel_hi:[1,0]
	ds_read_b128 v[42:45], v139 offset:27648
	ds_read_b128 v[54:57], v139 offset:35840
	s_waitcnt lgkmcnt(0)
	v_pk_fma_f32 v[56:57], v[44:45], v[46:47], v[56:57]
	v_pk_fma_f32 v[54:55], v[42:43], v[82:83], v[54:55]
	v_pk_mul_f32 v[82:83], v[48:49], v[80:81] op_sel_hi:[1,0]
	ds_read_b128 v[42:45], v139 offset:28672
	ds_read_b128 v[46:49], v139 offset:36864
	s_waitcnt lgkmcnt(0)
	v_pk_fma_f32 v[44:45], v[44:45], v[82:83], v[48:49]
	v_pk_fma_f32 v[42:43], v[42:43], v[58:59], v[46:47]
	v_pk_mul_f32 v[82:83], v[60:61], v[80:81] op_sel_hi:[1,0]
	ds_read_b128 v[46:49], v139 offset:29696
	ds_read_b128 v[58:61], v139 offset:37888
	s_waitcnt lgkmcnt(0)
	v_pk_fma_f32 v[60:61], v[48:49], v[82:83], v[60:61]
	v_pk_fma_f32 v[58:59], v[46:47], v[64:65], v[58:59]
	v_pk_mul_f32 v[82:83], v[62:63], v[80:81] op_sel_hi:[1,0]
	ds_read_b128 v[46:49], v139 offset:30720
	ds_read_b128 v[62:65], v139 offset:38912
	s_waitcnt lgkmcnt(0)
	v_pk_fma_f32 v[48:49], v[48:49], v[82:83], v[64:65]
	v_pk_fma_f32 v[46:47], v[46:47], v[78:79], v[62:63]
	v_pk_mul_f32 v[78:79], v[74:75], v[80:81] op_sel_hi:[1,0]
	v_pk_mul_f32 v[80:81], v[76:77], v[80:81] op_sel_hi:[1,0]
	ds_read_b128 v[62:65], v139 offset:31744
	ds_read_b128 v[74:77], v139 offset:39936
	global_store_dwordx4 v146, v[34:37], s[0:1]
	global_store_dwordx4 v146, v[50:53], s[0:1] offset:1024
	global_store_dwordx4 v146, v[38:41], s[0:1] offset:2048
	global_store_dwordx4 v146, v[54:57], s[0:1] offset:3072
	s_waitcnt lgkmcnt(0)
	v_pk_fma_f32 v[62:63], v[62:63], v[78:79], v[74:75]
	v_lshl_add_u64 v[74:75], s[0:1], 0, v[146:147]
	v_add_co_u32_e32 v74, vcc, 0x1000, v74
	v_readlane_b32 s0, v254, 21
	s_nop 0
	v_addc_co_u32_e32 v75, vcc, 0, v75, vcc
	v_readlane_b32 s1, v254, 22
	v_pk_fma_f32 v[64:65], v[64:65], v[80:81], v[76:77]
	s_andn2_b64 vcc, exec, s[0:1]
	global_store_dwordx4 v[74:75], v[42:45], off
	global_store_dwordx4 v[74:75], v[58:61], off offset:1024
	global_store_dwordx4 v[74:75], v[46:49], off offset:2048
	global_store_dwordx4 v[74:75], v[62:65], off offset:3072
	s_cbranch_vccnz .LBB0_2511
; #define LAS __attribute__((address_space(3)))
; __device__ __forceinline__ unsigned pk2(float lo, float hi) { return f2bf(lo) | (f2bf(hi) << 16); }
; __device__ __forceinline__ void store_mod_bf16_lds(bf16* orow, const f32x4 (&v)[8], const LAS float* sh, const LAS float* sc1p, int lane) {
; #pragma unroll
;     for (int j = 0; j < 8; ++j) { const int c = 256 * j + 4 * lane; const f32x4 s1 = *(const LAS f32x4*)(sc1p + c), s0 = *(const LAS f32x4*)(sh + c);
;         const f32x4 h = v[j] * s1 + s0; v2u w; w.x = pk2(h[0], h[1]); w.y = pk2(h[2], h[3]); *(v2u*)(orow + c) = w; }
; }
	v_lshl_add_u32 v92, s13, 2, v165
	ds_read_b128 v[74:77], v106 offset:40960
	ds_read_b128 v[78:81], v92
	ds_read_b128 v[82:85], v106 offset:41984
	ds_read_b128 v[86:89], v92 offset:1024
	s_lshl_b64 s[0:1], s[8:9], 12
	v_lshl_add_u64 v[90:91], v[72:73], 0, s[0:1]
	s_waitcnt lgkmcnt(2)
	v_pk_fma_f32 v[34:35], v[34:35], v[78:79], v[74:75]
	s_nop 0
	v_bfe_u32 v74, v34, 16, 1
	v_add3_u32 v34, v34, v74, s70
	v_bfe_u32 v74, v35, 16, 1
	v_pk_fma_f32 v[36:37], v[36:37], v[80:81], v[76:77]
	v_lshrrev_b32_e32 v34, 16, v34
	v_add3_u32 v35, v35, v74, s70
	v_and_or_b32 v34, v35, s33, v34
	v_bfe_u32 v35, v36, 16, 1
	v_add3_u32 v35, v36, v35, s70
	v_bfe_u32 v36, v37, 16, 1
	v_lshrrev_b32_e32 v35, 16, v35
	v_add3_u32 v36, v37, v36, s70
	v_and_or_b32 v35, v36, s33, v35
	s_waitcnt lgkmcnt(0)
	v_pk_fma_f32 v[36:37], v[50:51], v[86:87], v[82:83]
	global_store_dwordx2 v[90:91], v[34:35], off
	v_bfe_u32 v50, v36, 16, 1
	v_add3_u32 v36, v36, v50, s70
	v_bfe_u32 v50, v37, 16, 1
	v_pk_fma_f32 v[34:35], v[52:53], v[88:89], v[84:85]
	v_lshrrev_b32_e32 v36, 16, v36
	v_add3_u32 v37, v37, v50, s70
	v_and_or_b32 v74, v37, s33, v36
	v_bfe_u32 v36, v34, 16, 1
	v_add3_u32 v34, v34, v36, s70
	v_lshrrev_b32_e32 v75, 16, v34
	v_bfe_u32 v34, v35, 16, 1
	v_add3_u32 v76, v35, v34, s70
	ds_read_b128 v[34:37], v92 offset:2048
	ds_read_b128 v[50:53], v106 offset:43008
	v_and_or_b32 v75, v76, s33, v75
	global_store_dwordx2 v[90:91], v[74:75], off offset:512
	ds_read_b128 v[74:77], v92 offset:3072
	ds_read_b128 v[78:81], v106 offset:44032
	s_waitcnt lgkmcnt(2)
	v_pk_fma_f32 v[34:35], v[38:39], v[34:35], v[50:51]
	s_nop 0
	v_bfe_u32 v38, v34, 16, 1
	v_add3_u32 v34, v34, v38, s70
	v_bfe_u32 v38, v35, 16, 1
	v_pk_fma_f32 v[36:37], v[40:41], v[36:37], v[52:53]
	v_lshrrev_b32_e32 v34, 16, v34
	v_add3_u32 v35, v35, v38, s70
	v_and_or_b32 v34, v35, s33, v34
	v_bfe_u32 v35, v36, 16, 1
	v_add3_u32 v35, v36, v35, s70
	v_bfe_u32 v36, v37, 16, 1
	v_lshrrev_b32_e32 v35, 16, v35
	v_add3_u32 v36, v37, v36, s70
	v_and_or_b32 v35, v36, s33, v35
	s_waitcnt lgkmcnt(0)
	v_pk_fma_f32 v[36:37], v[54:55], v[74:75], v[78:79]
	global_store_dwordx2 v[90:91], v[34:35], off offset:1024
	v_bfe_u32 v38, v36, 16, 1
	v_add3_u32 v36, v36, v38, s70
	v_bfe_u32 v38, v37, 16, 1
	v_pk_fma_f32 v[34:35], v[56:57], v[76:77], v[80:81]
	v_lshrrev_b32_e32 v36, 16, v36
	v_add3_u32 v37, v37, v38, s70
	v_and_or_b32 v50, v37, s33, v36
	v_bfe_u32 v36, v34, 16, 1
	v_add3_u32 v34, v34, v36, s70
	v_lshrrev_b32_e32 v51, 16, v34
	v_bfe_u32 v34, v35, 16, 1
	v_add3_u32 v52, v35, v34, s70
	ds_read_b128 v[34:37], v92 offset:4096
	ds_read_b128 v[38:41], v106 offset:45056
	v_and_or_b32 v51, v52, s33, v51
	global_store_dwordx2 v[90:91], v[50:51], off offset:1536
	ds_read_b128 v[50:53], v92 offset:5120
	ds_read_b128 v[54:57], v106 offset:46080
	s_waitcnt lgkmcnt(2)
	v_pk_fma_f32 v[34:35], v[42:43], v[34:35], v[38:39]
	s_nop 0
	v_bfe_u32 v38, v34, 16, 1
	v_add3_u32 v34, v34, v38, s70
	v_bfe_u32 v38, v35, 16, 1
	v_pk_fma_f32 v[36:37], v[44:45], v[36:37], v[40:41]
	v_lshrrev_b32_e32 v34, 16, v34
	v_add3_u32 v35, v35, v38, s70
	v_and_or_b32 v34, v35, s33, v34
	v_bfe_u32 v35, v36, 16, 1
	v_add3_u32 v35, v36, v35, s70
	v_bfe_u32 v36, v37, 16, 1
	v_lshrrev_b32_e32 v35, 16, v35
	v_add3_u32 v36, v37, v36, s70
	v_and_or_b32 v35, v36, s33, v35
	s_waitcnt lgkmcnt(0)
	v_pk_fma_f32 v[36:37], v[58:59], v[50:51], v[54:55]
	global_store_dwordx2 v[90:91], v[34:35], off offset:2048
	v_bfe_u32 v38, v36, 16, 1
	v_add3_u32 v36, v36, v38, s70
	v_bfe_u32 v38, v37, 16, 1
	v_pk_fma_f32 v[34:35], v[60:61], v[52:53], v[56:57]
	v_lshrrev_b32_e32 v36, 16, v36
	v_add3_u32 v37, v37, v38, s70
	v_and_or_b32 v42, v37, s33, v36
	v_bfe_u32 v36, v34, 16, 1
	v_add3_u32 v34, v34, v36, s70
	v_lshrrev_b32_e32 v43, 16, v34
	v_bfe_u32 v34, v35, 16, 1
	v_add3_u32 v44, v35, v34, s70
	ds_read_b128 v[34:37], v92 offset:6144
	ds_read_b128 v[38:41], v106 offset:47104
	v_and_or_b32 v43, v44, s33, v43
	global_store_dwordx2 v[90:91], v[42:43], off offset:2560
	ds_read_b128 v[42:45], v92 offset:7168
	ds_read_b128 v[50:53], v106 offset:48128
	s_waitcnt lgkmcnt(2)
	v_pk_fma_f32 v[34:35], v[46:47], v[34:35], v[38:39]
	s_nop 0
	v_bfe_u32 v38, v34, 16, 1
	v_add3_u32 v34, v34, v38, s70
	v_bfe_u32 v38, v35, 16, 1
	v_pk_fma_f32 v[36:37], v[48:49], v[36:37], v[40:41]
	v_lshrrev_b32_e32 v34, 16, v34
	v_add3_u32 v35, v35, v38, s70
	v_and_or_b32 v34, v35, s33, v34
	v_bfe_u32 v35, v36, 16, 1
	v_add3_u32 v35, v36, v35, s70
	v_bfe_u32 v36, v37, 16, 1
	v_lshrrev_b32_e32 v35, 16, v35
	v_add3_u32 v36, v37, v36, s70
	v_and_or_b32 v35, v36, s33, v35
	s_waitcnt lgkmcnt(0)
	v_pk_fma_f32 v[36:37], v[62:63], v[42:43], v[50:51]
	global_store_dwordx2 v[90:91], v[34:35], off offset:3072
	v_bfe_u32 v38, v36, 16, 1
	v_add3_u32 v36, v36, v38, s70
	v_bfe_u32 v38, v37, 16, 1
	v_pk_fma_f32 v[34:35], v[64:65], v[44:45], v[52:53]
	v_lshrrev_b32_e32 v36, 16, v36
	v_add3_u32 v37, v37, v38, s70
	v_and_or_b32 v36, v37, s33, v36
	v_bfe_u32 v37, v34, 16, 1
	v_add3_u32 v34, v34, v37, s70
	v_bfe_u32 v37, v35, 16, 1
	v_lshrrev_b32_e32 v34, 16, v34
	v_add3_u32 v35, v35, v37, s70
	v_and_or_b32 v37, v35, s33, v34
	global_store_dwordx2 v[90:91], v[36:37], off offset:3584
	s_branch .LBB0_2511
